# P6 sample-row path: X1 write-back store of each chunk issued after the next chunk's loads (waits no longer include store completion)
# baseline (speedup 1.0000x reference)
.LBB0_1436:
	s_andn2_saveexec_b64 s[40:41], s[40:41]
	s_cbranch_execz .LBB0_1433
	v_add_u32_e32 v100, 0xffffe000, v130
	s_waitcnt vmcnt(7)
	v_lshlrev_b64 v[64:65], 13, v[100:101]
	s_waitcnt vmcnt(1)
	v_lshl_add_u64 v[90:91], s[70:71], 0, v[64:65]
	v_lshlrev_b64 v[64:65], 14, v[100:101]
	v_add_u32_e32 v100, 0xffffe200, v130
	v_lshl_add_u64 v[88:89], s[36:37], 0, v[64:65]
	v_lshlrev_b64 v[170:171], 14, v[100:101]
	v_add_u32_e32 v100, 0xffffe400, v130
	v_mov_b32_e32 v133, v101
	s_waitcnt vmcnt(0)
	v_lshlrev_b64 v[94:95], 14, v[100:101]
	v_lshl_add_u64 v[174:175], v[88:89], 0, v[132:133]
	v_lshl_add_u64 v[68:69], v[116:117], 0, v[170:171]
	v_add_u32_e32 v100, 0xffffe600, v130
	global_load_dwordx4 v[64:67], v[174:175], off
	s_nop 0
	global_load_dwordx4 v[68:71], v[68:69], off
	v_lshl_add_u64 v[72:73], v[116:117], 0, v[94:95]
	v_lshlrev_b64 v[92:93], 14, v[100:101]
	global_load_dwordx4 v[72:75], v[72:73], off
	v_lshl_add_u64 v[76:77], v[116:117], 0, v[92:93]
	v_lshl_add_u64 v[172:173], v[90:91], 0, v[132:133]
	global_load_dwordx4 v[76:79], v[76:77], off
	s_nop 0
	global_load_dwordx4 v[80:83], v[134:135], off
	global_load_dwordx4 v[84:87], v[172:173], off
	v_add_co_u32_e32 v176, vcc, s61, v168
	v_mov_b32_e32 v137, v101
	s_nop 0
	v_addc_co_u32_e32 v177, vcc, 0, v169, vcc
	v_lshl_add_u64 v[186:187], s[36:37], 0, v[170:171]
	v_lshl_add_u64 v[188:189], s[36:37], 0, v[94:95]
	v_lshl_add_u64 v[178:179], v[186:187], 0, v[136:137]
	v_lshl_add_u64 v[180:181], v[188:189], 0, v[136:137]
	v_lshl_add_u64 v[190:191], s[36:37], 0, v[92:93]
	v_mov_b32_e32 v141, v101
	v_lshl_add_u64 v[182:183], v[186:187], 0, v[140:141]
	v_mov_b32_e32 v145, v101
	v_lshl_add_u64 v[186:187], v[186:187], 0, v[144:145]
	v_mov_b32_e32 v149, v101
	v_mov_b32_e32 v153, v101
	v_lshl_add_u64 v[194:195], v[120:121], 0, v[170:171]
	v_mov_b32_e32 v157, v101
	v_lshl_add_u64 v[198:199], v[122:123], 0, v[170:171]
	v_mov_b32_e32 v161, v101
	s_waitcnt vmcnt(4)
	v_pk_add_f32 v[66:67], v[66:67], v[70:71]
	v_pk_add_f32 v[64:65], v[64:65], v[68:69]
	s_waitcnt vmcnt(3)
	v_pk_add_f32 v[66:67], v[66:67], v[74:75]
	v_pk_add_f32 v[64:65], v[64:65], v[72:73]
	s_waitcnt vmcnt(2)
	v_pk_add_f32 v[66:67], v[66:67], v[78:79]
	v_pk_add_f32 v[64:65], v[64:65], v[76:77]
	s_waitcnt vmcnt(0)
	v_pk_fma_f32 v[66:67], v[82:83], v[66:67], v[86:87]
	v_pk_fma_f32 v[64:65], v[80:81], v[64:65], v[84:85]
	global_load_dwordx4 v[68:71], v[174:175], off offset:1024
	global_load_dwordx4 v[72:75], v[178:179], off
	global_load_dwordx4 v[76:79], v[180:181], off
	v_lshl_add_u64 v[80:81], v[190:191], 0, v[136:137]
	global_load_dwordx4 v[80:83], v[80:81], off
	s_nop 0
	global_load_dwordx4 v[84:87], v[172:173], off offset:1024
	global_load_dwordx4 v[178:181], v[138:139], off
	global_store_dwordx4 v[176:177], v[64:67], off offset:1792
	s_waitcnt vmcnt(5)
	v_pk_add_f32 v[70:71], v[70:71], v[74:75]
	v_pk_add_f32 v[68:69], v[68:69], v[72:73]
	s_waitcnt vmcnt(4)
	v_pk_add_f32 v[70:71], v[70:71], v[78:79]
	v_pk_add_f32 v[68:69], v[68:69], v[76:77]
	s_waitcnt vmcnt(3)
	v_pk_add_f32 v[70:71], v[70:71], v[82:83]
	v_pk_add_f32 v[68:69], v[68:69], v[80:81]
	s_waitcnt vmcnt(1)
	v_pk_fma_f32 v[70:71], v[180:181], v[70:71], v[86:87]
	v_pk_fma_f32 v[68:69], v[178:179], v[68:69], v[84:85]
	global_load_dwordx4 v[72:75], v[174:175], off offset:2048
	global_load_dwordx4 v[76:79], v[182:183], off
	v_lshl_add_u64 v[80:81], v[188:189], 0, v[140:141]
	global_load_dwordx4 v[80:83], v[80:81], off
	v_lshl_add_u64 v[84:85], v[190:191], 0, v[140:141]
	global_load_dwordx4 v[84:87], v[84:85], off
	s_nop 0
	global_load_dwordx4 v[178:181], v[172:173], off offset:2048
	global_load_dwordx4 v[182:185], v[142:143], off
	global_store_dwordx4 v[176:177], v[68:71], off offset:2816
	s_waitcnt vmcnt(5)
	v_pk_add_f32 v[74:75], v[74:75], v[78:79]
	v_pk_add_f32 v[72:73], v[72:73], v[76:77]
	s_waitcnt vmcnt(4)
	v_pk_add_f32 v[74:75], v[74:75], v[82:83]
	v_pk_add_f32 v[72:73], v[72:73], v[80:81]
	s_waitcnt vmcnt(3)
	v_pk_add_f32 v[74:75], v[74:75], v[86:87]
	v_pk_add_f32 v[72:73], v[72:73], v[84:85]
	s_waitcnt vmcnt(1)
	v_pk_fma_f32 v[74:75], v[184:185], v[74:75], v[180:181]
	v_pk_fma_f32 v[72:73], v[182:183], v[72:73], v[178:179]
	global_load_dwordx4 v[76:79], v[174:175], off offset:3072
	global_load_dwordx4 v[80:83], v[186:187], off
	v_lshl_add_u64 v[84:85], v[188:189], 0, v[144:145]
	global_load_dwordx4 v[84:87], v[84:85], off
	v_lshl_add_u64 v[174:175], v[190:191], 0, v[144:145]
	global_load_dwordx4 v[178:181], v[174:175], off
	global_load_dwordx4 v[182:185], v[172:173], off offset:3072
	global_load_dwordx4 v[186:189], v[146:147], off
	global_store_dwordx4 v[176:177], v[72:75], off offset:3840
	v_add_co_u32_e32 v172, vcc, s62, v168
	v_lshl_add_u64 v[176:177], v[88:89], 0, v[148:149]
	s_nop 0
	v_addc_co_u32_e32 v173, vcc, 0, v169, vcc
	v_lshl_add_u64 v[190:191], v[118:119], 0, v[170:171]
	v_lshl_add_u64 v[174:175], v[90:91], 0, v[148:149]
	v_lshl_add_u64 v[170:171], v[124:125], 0, v[170:171]
	v_add_co_u32_e32 v168, vcc, 0x2094f000, v168
	s_waitcnt vmcnt(5)
	v_pk_add_f32 v[78:79], v[78:79], v[82:83]
	v_pk_add_f32 v[76:77], v[76:77], v[80:81]
	s_waitcnt vmcnt(4)
	v_pk_add_f32 v[78:79], v[78:79], v[86:87]
	v_pk_add_f32 v[76:77], v[76:77], v[84:85]
	s_waitcnt vmcnt(3)
	v_pk_add_f32 v[78:79], v[78:79], v[180:181]
	v_pk_add_f32 v[76:77], v[76:77], v[178:179]
	s_waitcnt vmcnt(1)
	v_pk_fma_f32 v[78:79], v[188:189], v[78:79], v[184:185]
	v_pk_fma_f32 v[76:77], v[186:187], v[76:77], v[182:183]
	global_load_dwordx4 v[80:83], v[176:177], off
	global_load_dwordx4 v[84:87], v[190:191], off
	v_lshl_add_u64 v[176:177], v[118:119], 0, v[94:95]
	global_load_dwordx4 v[178:181], v[176:177], off
	v_lshl_add_u64 v[176:177], v[118:119], 0, v[92:93]
	global_load_dwordx4 v[182:185], v[176:177], off
	global_load_dwordx4 v[186:189], v[174:175], off
	global_load_dwordx4 v[190:193], v[150:151], off
	global_store_dwordx4 v[172:173], v[76:79], off offset:768
	v_lshl_add_u64 v[176:177], v[88:89], 0, v[152:153]
	v_lshl_add_u64 v[174:175], v[90:91], 0, v[152:153]
	v_addc_co_u32_e32 v169, vcc, 0, v169, vcc
	s_waitcnt vmcnt(5)
	v_pk_add_f32 v[82:83], v[82:83], v[86:87]
	v_pk_add_f32 v[80:81], v[80:81], v[84:85]
	s_waitcnt vmcnt(4)
	v_pk_add_f32 v[82:83], v[82:83], v[180:181]
	v_pk_add_f32 v[80:81], v[80:81], v[178:179]
	s_waitcnt vmcnt(3)
	v_pk_add_f32 v[82:83], v[82:83], v[184:185]
	v_pk_add_f32 v[80:81], v[80:81], v[182:183]
	s_waitcnt vmcnt(1)
	v_pk_fma_f32 v[82:83], v[192:193], v[82:83], v[188:189]
	v_pk_fma_f32 v[80:81], v[190:191], v[80:81], v[186:187]
	global_load_dwordx4 v[84:87], v[176:177], off
	global_load_dwordx4 v[178:181], v[194:195], off
	v_lshl_add_u64 v[176:177], v[120:121], 0, v[94:95]
	global_load_dwordx4 v[182:185], v[176:177], off
	v_lshl_add_u64 v[176:177], v[120:121], 0, v[92:93]
	global_load_dwordx4 v[186:189], v[176:177], off
	global_load_dwordx4 v[190:193], v[174:175], off
	global_load_dwordx4 v[194:197], v[154:155], off
	global_store_dwordx4 v[172:173], v[80:83], off offset:1792
	v_lshl_add_u64 v[176:177], v[88:89], 0, v[156:157]
	v_lshl_add_u64 v[174:175], v[90:91], 0, v[156:157]
	s_waitcnt vmcnt(5)
	v_pk_add_f32 v[86:87], v[86:87], v[180:181]
	v_pk_add_f32 v[84:85], v[84:85], v[178:179]
	s_waitcnt vmcnt(4)
	v_pk_add_f32 v[86:87], v[86:87], v[184:185]
	v_pk_add_f32 v[84:85], v[84:85], v[182:183]
	s_waitcnt vmcnt(3)
	v_pk_add_f32 v[86:87], v[86:87], v[188:189]
	v_pk_add_f32 v[84:85], v[84:85], v[186:187]
	s_waitcnt vmcnt(1)
	v_pk_fma_f32 v[86:87], v[196:197], v[86:87], v[192:193]
	v_pk_fma_f32 v[84:85], v[194:195], v[84:85], v[190:191]
	global_load_dwordx4 v[178:181], v[176:177], off
	global_load_dwordx4 v[182:185], v[198:199], off
	v_lshl_add_u64 v[176:177], v[122:123], 0, v[94:95]
	global_load_dwordx4 v[186:189], v[176:177], off
	v_lshl_add_u64 v[176:177], v[122:123], 0, v[92:93]
	global_load_dwordx4 v[190:193], v[176:177], off
	global_load_dwordx4 v[194:197], v[174:175], off
	global_load_dwordx4 v[198:201], v[158:159], off
	global_store_dwordx4 v[172:173], v[84:87], off offset:2816
	v_lshl_add_u64 v[174:175], v[90:91], 0, v[160:161]
	v_lshl_add_u64 v[176:177], v[88:89], 0, v[160:161]
	v_lshl_add_u64 v[94:95], v[124:125], 0, v[94:95]
	v_lshl_add_u64 v[92:93], v[124:125], 0, v[92:93]
	s_waitcnt vmcnt(5)
	v_pk_add_f32 v[88:89], v[180:181], v[184:185]
	v_pk_add_f32 v[90:91], v[178:179], v[182:183]
	s_waitcnt vmcnt(4)
	v_pk_add_f32 v[88:89], v[88:89], v[188:189]
	v_pk_add_f32 v[90:91], v[90:91], v[186:187]
	s_waitcnt vmcnt(3)
	v_pk_add_f32 v[88:89], v[88:89], v[192:193]
	v_pk_add_f32 v[178:179], v[90:91], v[190:191]
	s_waitcnt vmcnt(1)
	v_pk_fma_f32 v[90:91], v[200:201], v[88:89], v[196:197]
	v_pk_fma_f32 v[88:89], v[198:199], v[178:179], v[194:195]
	global_load_dwordx4 v[178:181], v[176:177], off
	global_load_dwordx4 v[182:185], v[170:171], off
	global_load_dwordx4 v[186:189], v[94:95], off
	s_nop 0
	global_load_dwordx4 v[92:95], v[92:93], off
	s_nop 0
	global_load_dwordx4 v[190:193], v[174:175], off
	global_load_dwordx4 v[194:197], v[162:163], off
	global_store_dwordx4 v[172:173], v[88:91], off offset:3840
	s_waitcnt vmcnt(5)
	v_pk_add_f32 v[170:171], v[180:181], v[184:185]
	v_pk_add_f32 v[172:173], v[178:179], v[182:183]
	s_waitcnt vmcnt(4)
	v_pk_add_f32 v[170:171], v[170:171], v[188:189]
	v_pk_add_f32 v[172:173], v[172:173], v[186:187]
	s_waitcnt vmcnt(3)
	v_pk_add_f32 v[94:95], v[170:171], v[94:95]
	v_pk_add_f32 v[92:93], v[172:173], v[92:93]
	s_waitcnt vmcnt(1)
	v_pk_fma_f32 v[94:95], v[196:197], v[94:95], v[192:193]
	v_pk_fma_f32 v[92:93], v[194:195], v[92:93], v[190:191]
	global_store_dwordx4 v[168:169], v[92:95], off offset:768
	s_branch .LBB0_1433
